# phase F SwiGLU output (MID) written with non-temporal stores
# speedup vs baseline: 1.0051x; 1.0051x over previous
.LBB0_513:
	v_lshl_add_u32 v152, s8, 10, v148
	ds_read_b32 v154, v152
	v_lshl_or_b32 v142, s10, 7, v149
	v_lshl_add_u32 v151, s9, 8, v146
	v_ashrrev_i32_e32 v143, 31, v142
	v_mov_b64_e32 v[140:141], s[4:5]
	s_waitcnt lgkmcnt(0)
	v_pk_mul_f32 v[126:127], v[126:127], v[154:155] op_sel_hi:[1,0]
	v_pk_mul_f32 v[118:119], v[118:119], v[154:155] op_sel_hi:[1,0]
	v_pk_mul_f32 v[156:157], v[116:117], v[154:155] op_sel_hi:[1,0]
	v_pk_mul_f32 v[116:117], v[114:115], v[154:155] op_sel_hi:[1,0]
	v_mul_f32_e32 v115, 0xbfb8aa3b, v126
	v_mul_f32_e32 v114, v126, v118
	v_exp_f32_e32 v115, v115
	v_mul_f32_e32 v118, 0xbfb8aa3b, v127
	v_exp_f32_e32 v118, v118
	v_pk_mul_f32 v[128:129], v[128:129], v[154:155] op_sel_hi:[1,0]
	v_add_f32_e32 v115, 1.0, v115
	v_rcp_f32_e32 v115, v115
	v_add_f32_e32 v118, 1.0, v118
	v_rcp_f32_e32 v118, v118
	v_pk_mul_f32 v[120:121], v[120:121], v[154:155] op_sel_hi:[1,0]
	v_mul_f32_e32 v114, v114, v115
	v_mul_f32_e32 v115, v127, v119
	v_mul_f32_e32 v115, v115, v118
	v_mul_f32_e32 v118, 0xbfb8aa3b, v128
	v_exp_f32_e32 v118, v118
	v_mul_f32_e32 v119, 0xbfb8aa3b, v129
	v_exp_f32_e32 v119, v119
	v_cvt_pk_bf16_f32 v114, v114, v115
	v_add_f32_e32 v118, 1.0, v118
	v_rcp_f32_e32 v118, v118
	v_add_f32_e32 v119, 1.0, v119
	v_rcp_f32_e32 v119, v119
	v_mul_f32_e32 v115, v128, v120
	v_mul_f32_e32 v115, v115, v118
	v_mul_f32_e32 v118, v129, v121
	v_pk_mul_f32 v[122:123], v[122:123], v[154:155] op_sel_hi:[1,0]
	v_mul_f32_e32 v118, v118, v119
	v_cvt_pk_bf16_f32 v115, v115, v118
	v_mul_f32_e32 v118, 0xbfb8aa3b, v122
	v_exp_f32_e32 v118, v118
	v_mul_f32_e32 v116, v122, v116
	v_pk_mul_f32 v[124:125], v[124:125], v[154:155] op_sel_hi:[1,0]
	v_mul_f32_e32 v117, v123, v117
	v_add_f32_e32 v118, 1.0, v118
	v_rcp_f32_e32 v118, v118
	v_mul_f32_e32 v119, 0xbfb8aa3b, v125
	v_exp_f32_e32 v119, v119
	v_mad_i64_i32 v[144:145], s[10:11], v151, s26, v[140:141]
	v_mul_f32_e32 v116, v116, v118
	v_mul_f32_e32 v118, 0xbfb8aa3b, v123
	v_exp_f32_e32 v118, v118
	v_add_f32_e32 v119, 1.0, v119
	v_rcp_f32_e32 v119, v119
	v_lshlrev_b64 v[142:143], 1, v[142:143]
	v_add_f32_e32 v118, 1.0, v118
	v_rcp_f32_e32 v118, v118
	v_lshl_add_u64 v[144:145], v[144:145], 0, v[142:143]
	s_mov_b64 s[56:57], -1
	s_andn2_b64 vcc, exec, s[40:41]
	v_mul_f32_e32 v117, v117, v118
	v_mul_f32_e32 v118, 0xbfb8aa3b, v124
	v_exp_f32_e32 v118, v118
	v_cvt_pk_bf16_f32 v116, v116, v117
	v_mul_f32_e32 v117, v124, v156
	v_add_f32_e32 v118, 1.0, v118
	v_rcp_f32_e32 v118, v118
	s_nop 0
	v_mul_f32_e32 v117, v117, v118
	v_mul_f32_e32 v118, v125, v157
	v_mul_f32_e32 v118, v118, v119
	v_cvt_pk_bf16_f32 v117, v117, v118
	global_store_dwordx4 v[144:145], v[114:117], off nt
	ds_read_b32 v116, v152 offset:64
	s_waitcnt lgkmcnt(0)
	v_pk_mul_f32 v[110:111], v[110:111], v[116:117] op_sel_hi:[1,0]
	v_pk_mul_f32 v[102:103], v[102:103], v[116:117] op_sel_hi:[1,0]
	v_pk_mul_f32 v[118:119], v[100:101], v[116:117] op_sel_hi:[1,0]
	v_pk_mul_f32 v[100:101], v[98:99], v[116:117] op_sel_hi:[1,0]
	v_mul_f32_e32 v99, 0xbfb8aa3b, v110
	v_mul_f32_e32 v98, v110, v102
	v_exp_f32_e32 v99, v99
	v_mul_f32_e32 v102, 0xbfb8aa3b, v111
	v_exp_f32_e32 v102, v102
	v_pk_mul_f32 v[112:113], v[112:113], v[116:117] op_sel_hi:[1,0]
	v_add_f32_e32 v99, 1.0, v99
	v_rcp_f32_e32 v99, v99
	v_add_f32_e32 v102, 1.0, v102
	v_rcp_f32_e32 v102, v102
	v_pk_mul_f32 v[104:105], v[104:105], v[116:117] op_sel_hi:[1,0]
	v_mul_f32_e32 v98, v98, v99
	v_mul_f32_e32 v99, v111, v103
	v_mul_f32_e32 v99, v99, v102
	v_mul_f32_e32 v102, 0xbfb8aa3b, v112
	v_exp_f32_e32 v102, v102
	v_mul_f32_e32 v103, 0xbfb8aa3b, v113
	v_exp_f32_e32 v103, v103
	v_cvt_pk_bf16_f32 v98, v98, v99
	v_add_f32_e32 v102, 1.0, v102
	v_rcp_f32_e32 v102, v102
	v_add_f32_e32 v103, 1.0, v103
	v_rcp_f32_e32 v103, v103
	v_mul_f32_e32 v99, v112, v104
	v_mul_f32_e32 v99, v99, v102
	v_mul_f32_e32 v102, v113, v105
	v_pk_mul_f32 v[106:107], v[106:107], v[116:117] op_sel_hi:[1,0]
	v_mul_f32_e32 v102, v102, v103
	v_cvt_pk_bf16_f32 v99, v99, v102
	v_mul_f32_e32 v102, 0xbfb8aa3b, v106
	v_exp_f32_e32 v102, v102
	v_mul_f32_e32 v100, v106, v100
	v_pk_mul_f32 v[108:109], v[108:109], v[116:117] op_sel_hi:[1,0]
	v_mul_f32_e32 v101, v107, v101
	v_add_f32_e32 v102, 1.0, v102
	v_rcp_f32_e32 v102, v102
	v_mul_f32_e32 v103, 0xbfb8aa3b, v109
	v_exp_f32_e32 v103, v103
	v_or_b32_e32 v114, 16, v151
	v_mul_f32_e32 v100, v100, v102
	v_mul_f32_e32 v102, 0xbfb8aa3b, v107
	v_exp_f32_e32 v102, v102
	v_add_f32_e32 v103, 1.0, v103
	v_rcp_f32_e32 v103, v103
	v_mad_i64_i32 v[114:115], s[8:9], v114, s26, v[140:141]
	v_add_f32_e32 v102, 1.0, v102
	v_rcp_f32_e32 v102, v102
	v_lshl_add_u64 v[114:115], v[114:115], 0, v[142:143]
	v_mul_f32_e32 v101, v101, v102
	v_mul_f32_e32 v102, 0xbfb8aa3b, v108
	v_exp_f32_e32 v102, v102
	v_cvt_pk_bf16_f32 v100, v100, v101
	v_mul_f32_e32 v101, v108, v118
	v_add_f32_e32 v102, 1.0, v102
	v_rcp_f32_e32 v102, v102
	s_nop 0
	v_mul_f32_e32 v101, v101, v102
	v_mul_f32_e32 v102, v109, v119
	v_mul_f32_e32 v102, v102, v103
	v_cvt_pk_bf16_f32 v101, v101, v102
	global_store_dwordx4 v[114:115], v[98:101], off nt
	ds_read_b32 v100, v152 offset:128
	s_waitcnt lgkmcnt(0)
	v_pk_mul_f32 v[94:95], v[94:95], v[100:101] op_sel_hi:[1,0]
	v_pk_mul_f32 v[86:87], v[86:87], v[100:101] op_sel_hi:[1,0]
	v_pk_mul_f32 v[102:103], v[84:85], v[100:101] op_sel_hi:[1,0]
	v_pk_mul_f32 v[84:85], v[82:83], v[100:101] op_sel_hi:[1,0]
	v_mul_f32_e32 v83, 0xbfb8aa3b, v94
	v_mul_f32_e32 v82, v94, v86
	v_exp_f32_e32 v83, v83
	v_mul_f32_e32 v86, 0xbfb8aa3b, v95
	v_exp_f32_e32 v86, v86
	v_pk_mul_f32 v[96:97], v[96:97], v[100:101] op_sel_hi:[1,0]
	v_add_f32_e32 v83, 1.0, v83
	v_rcp_f32_e32 v83, v83
	v_add_f32_e32 v86, 1.0, v86
	v_rcp_f32_e32 v86, v86
	v_pk_mul_f32 v[88:89], v[88:89], v[100:101] op_sel_hi:[1,0]
	v_mul_f32_e32 v82, v82, v83
	v_mul_f32_e32 v83, v95, v87
	v_mul_f32_e32 v83, v83, v86
	v_mul_f32_e32 v86, 0xbfb8aa3b, v96
	v_exp_f32_e32 v86, v86
	v_mul_f32_e32 v87, 0xbfb8aa3b, v97
	v_exp_f32_e32 v87, v87
	v_cvt_pk_bf16_f32 v82, v82, v83
	v_add_f32_e32 v86, 1.0, v86
	v_rcp_f32_e32 v86, v86
	v_add_f32_e32 v87, 1.0, v87
	v_rcp_f32_e32 v87, v87
	v_mul_f32_e32 v83, v96, v88
	v_mul_f32_e32 v83, v83, v86
	v_mul_f32_e32 v86, v97, v89
	v_pk_mul_f32 v[90:91], v[90:91], v[100:101] op_sel_hi:[1,0]
	v_mul_f32_e32 v86, v86, v87
	v_cvt_pk_bf16_f32 v83, v83, v86
	v_mul_f32_e32 v86, 0xbfb8aa3b, v90
	v_exp_f32_e32 v86, v86
	v_mul_f32_e32 v84, v90, v84
	v_pk_mul_f32 v[92:93], v[92:93], v[100:101] op_sel_hi:[1,0]
	v_mul_f32_e32 v85, v91, v85
	v_add_f32_e32 v86, 1.0, v86
	v_rcp_f32_e32 v86, v86
	v_mul_f32_e32 v87, 0xbfb8aa3b, v93
	v_exp_f32_e32 v87, v87
	v_or_b32_e32 v98, 32, v151
	v_mul_f32_e32 v84, v84, v86
	v_mul_f32_e32 v86, 0xbfb8aa3b, v91
	v_exp_f32_e32 v86, v86
	v_add_f32_e32 v87, 1.0, v87
	v_rcp_f32_e32 v87, v87
	v_mad_i64_i32 v[98:99], s[8:9], v98, s26, v[140:141]
	v_add_f32_e32 v86, 1.0, v86
	v_rcp_f32_e32 v86, v86
	v_lshl_add_u64 v[98:99], v[98:99], 0, v[142:143]
	v_mul_f32_e32 v85, v85, v86
	v_mul_f32_e32 v86, 0xbfb8aa3b, v92
	v_exp_f32_e32 v86, v86
	v_cvt_pk_bf16_f32 v84, v84, v85
	v_mul_f32_e32 v85, v92, v102
	v_add_f32_e32 v86, 1.0, v86
	v_rcp_f32_e32 v86, v86
	s_nop 0
	v_mul_f32_e32 v85, v85, v86
	v_mul_f32_e32 v86, v93, v103
	v_mul_f32_e32 v86, v86, v87
	v_cvt_pk_bf16_f32 v85, v85, v86
	global_store_dwordx4 v[98:99], v[82:85], off nt
	ds_read_b32 v84, v152 offset:192
	s_waitcnt lgkmcnt(0)
	v_pk_mul_f32 v[78:79], v[78:79], v[84:85] op_sel_hi:[1,0]
	v_pk_mul_f32 v[70:71], v[70:71], v[84:85] op_sel_hi:[1,0]
	v_pk_mul_f32 v[86:87], v[68:69], v[84:85] op_sel_hi:[1,0]
	v_pk_mul_f32 v[68:69], v[66:67], v[84:85] op_sel_hi:[1,0]
	v_mul_f32_e32 v67, 0xbfb8aa3b, v78
	v_mul_f32_e32 v66, v78, v70
	v_exp_f32_e32 v67, v67
	v_mul_f32_e32 v70, 0xbfb8aa3b, v79
	v_exp_f32_e32 v70, v70
	v_pk_mul_f32 v[80:81], v[80:81], v[84:85] op_sel_hi:[1,0]
	v_add_f32_e32 v67, 1.0, v67
	v_rcp_f32_e32 v67, v67
	v_add_f32_e32 v70, 1.0, v70
	v_rcp_f32_e32 v70, v70
	v_pk_mul_f32 v[72:73], v[72:73], v[84:85] op_sel_hi:[1,0]
	v_mul_f32_e32 v66, v66, v67
	v_mul_f32_e32 v67, v79, v71
	v_mul_f32_e32 v67, v67, v70
	v_mul_f32_e32 v70, 0xbfb8aa3b, v80
	v_exp_f32_e32 v70, v70
	v_mul_f32_e32 v71, 0xbfb8aa3b, v81
	v_exp_f32_e32 v71, v71
	v_cvt_pk_bf16_f32 v66, v66, v67
	v_add_f32_e32 v70, 1.0, v70
	v_rcp_f32_e32 v70, v70
	v_add_f32_e32 v71, 1.0, v71
	v_rcp_f32_e32 v71, v71
	v_mul_f32_e32 v67, v80, v72
	v_mul_f32_e32 v67, v67, v70
	v_mul_f32_e32 v70, v81, v73
	v_pk_mul_f32 v[74:75], v[74:75], v[84:85] op_sel_hi:[1,0]
	v_mul_f32_e32 v70, v70, v71
	v_cvt_pk_bf16_f32 v67, v67, v70
	v_mul_f32_e32 v70, 0xbfb8aa3b, v74
	v_exp_f32_e32 v70, v70
	v_mul_f32_e32 v68, v74, v68
	v_pk_mul_f32 v[76:77], v[76:77], v[84:85] op_sel_hi:[1,0]
	v_mul_f32_e32 v69, v75, v69
	v_add_f32_e32 v70, 1.0, v70
	v_rcp_f32_e32 v70, v70
	v_mul_f32_e32 v71, 0xbfb8aa3b, v77
	v_exp_f32_e32 v71, v71
	v_or_b32_e32 v82, 48, v151
	v_mul_f32_e32 v68, v68, v70
	v_mul_f32_e32 v70, 0xbfb8aa3b, v75
	v_exp_f32_e32 v70, v70
	v_add_f32_e32 v71, 1.0, v71
	v_rcp_f32_e32 v71, v71
	v_mad_i64_i32 v[82:83], s[8:9], v82, s26, v[140:141]
	v_add_f32_e32 v70, 1.0, v70
	v_rcp_f32_e32 v70, v70
	v_lshl_add_u64 v[82:83], v[82:83], 0, v[142:143]
	v_mul_f32_e32 v69, v69, v70
	v_mul_f32_e32 v70, 0xbfb8aa3b, v76
	v_exp_f32_e32 v70, v70
	v_cvt_pk_bf16_f32 v68, v68, v69
	v_mul_f32_e32 v69, v76, v86
	v_add_f32_e32 v70, 1.0, v70
	v_rcp_f32_e32 v70, v70
	s_nop 0
	v_mul_f32_e32 v69, v69, v70
	v_mul_f32_e32 v70, v77, v87
	v_mul_f32_e32 v70, v70, v71
	v_cvt_pk_bf16_f32 v69, v69, v70
	global_store_dwordx4 v[82:83], v[66:69], off nt
	ds_read_b32 v68, v152 offset:512
	s_waitcnt lgkmcnt(0)
	v_pk_mul_f32 v[62:63], v[62:63], v[68:69] op_sel_hi:[1,0]
	v_pk_mul_f32 v[54:55], v[54:55], v[68:69] op_sel_hi:[1,0]
	v_pk_mul_f32 v[70:71], v[52:53], v[68:69] op_sel_hi:[1,0]
	v_pk_mul_f32 v[52:53], v[50:51], v[68:69] op_sel_hi:[1,0]
	v_mul_f32_e32 v51, 0xbfb8aa3b, v62
	v_mul_f32_e32 v50, v62, v54
	v_exp_f32_e32 v51, v51
	v_mul_f32_e32 v54, 0xbfb8aa3b, v63
	v_exp_f32_e32 v54, v54
	v_pk_mul_f32 v[64:65], v[64:65], v[68:69] op_sel_hi:[1,0]
	v_add_f32_e32 v51, 1.0, v51
	v_rcp_f32_e32 v51, v51
	v_add_f32_e32 v54, 1.0, v54
	v_rcp_f32_e32 v54, v54
	v_pk_mul_f32 v[56:57], v[56:57], v[68:69] op_sel_hi:[1,0]
	v_mul_f32_e32 v50, v50, v51
	v_mul_f32_e32 v51, v63, v55
	v_mul_f32_e32 v51, v51, v54
	v_mul_f32_e32 v54, 0xbfb8aa3b, v64
	v_exp_f32_e32 v54, v54
	v_mul_f32_e32 v55, 0xbfb8aa3b, v65
	v_exp_f32_e32 v55, v55
	v_cvt_pk_bf16_f32 v50, v50, v51
	v_add_f32_e32 v54, 1.0, v54
	v_rcp_f32_e32 v54, v54
	v_add_f32_e32 v55, 1.0, v55
	v_rcp_f32_e32 v55, v55
	v_mul_f32_e32 v51, v64, v56
	v_mul_f32_e32 v51, v51, v54
	v_mul_f32_e32 v54, v65, v57
	v_pk_mul_f32 v[58:59], v[58:59], v[68:69] op_sel_hi:[1,0]
	v_mul_f32_e32 v54, v54, v55
	v_cvt_pk_bf16_f32 v51, v51, v54
	v_mul_f32_e32 v54, 0xbfb8aa3b, v58
	v_exp_f32_e32 v54, v54
	v_mul_f32_e32 v52, v58, v52
	v_pk_mul_f32 v[60:61], v[60:61], v[68:69] op_sel_hi:[1,0]
	v_mul_f32_e32 v53, v59, v53
	v_add_f32_e32 v54, 1.0, v54
	v_rcp_f32_e32 v54, v54
	v_mul_f32_e32 v55, 0xbfb8aa3b, v61
	v_exp_f32_e32 v55, v55
	v_add_u32_e32 v66, 0x80, v151
	v_mul_f32_e32 v52, v52, v54
	v_mul_f32_e32 v54, 0xbfb8aa3b, v59
	v_exp_f32_e32 v54, v54
	v_add_f32_e32 v55, 1.0, v55
	v_rcp_f32_e32 v55, v55
	v_mad_i64_i32 v[66:67], s[8:9], v66, s26, v[140:141]
	v_add_f32_e32 v54, 1.0, v54
	v_rcp_f32_e32 v54, v54
	v_lshl_add_u64 v[66:67], v[66:67], 0, v[142:143]
	v_mul_f32_e32 v53, v53, v54
	v_mul_f32_e32 v54, 0xbfb8aa3b, v60
	v_exp_f32_e32 v54, v54
	v_cvt_pk_bf16_f32 v52, v52, v53
	v_mul_f32_e32 v53, v60, v70
	v_add_f32_e32 v54, 1.0, v54
	v_rcp_f32_e32 v54, v54
	s_nop 0
	v_mul_f32_e32 v53, v53, v54
	v_mul_f32_e32 v54, v61, v71
	v_mul_f32_e32 v54, v54, v55
	v_cvt_pk_bf16_f32 v53, v53, v54
	global_store_dwordx4 v[66:67], v[50:53], off nt
	ds_read_b32 v52, v152 offset:576
	s_waitcnt lgkmcnt(0)
	v_pk_mul_f32 v[46:47], v[46:47], v[52:53] op_sel_hi:[1,0]
	v_pk_mul_f32 v[38:39], v[38:39], v[52:53] op_sel_hi:[1,0]
	v_pk_mul_f32 v[54:55], v[36:37], v[52:53] op_sel_hi:[1,0]
	v_pk_mul_f32 v[36:37], v[34:35], v[52:53] op_sel_hi:[1,0]
	v_mul_f32_e32 v35, 0xbfb8aa3b, v46
	v_mul_f32_e32 v34, v46, v38
	v_exp_f32_e32 v35, v35
	v_mul_f32_e32 v38, 0xbfb8aa3b, v47
	v_exp_f32_e32 v38, v38
	v_pk_mul_f32 v[48:49], v[48:49], v[52:53] op_sel_hi:[1,0]
	v_add_f32_e32 v35, 1.0, v35
	v_rcp_f32_e32 v35, v35
	v_add_f32_e32 v38, 1.0, v38
	v_rcp_f32_e32 v38, v38
	v_pk_mul_f32 v[40:41], v[40:41], v[52:53] op_sel_hi:[1,0]
	v_mul_f32_e32 v34, v34, v35
	v_mul_f32_e32 v35, v47, v39
	v_mul_f32_e32 v35, v35, v38
	v_mul_f32_e32 v38, 0xbfb8aa3b, v48
	v_exp_f32_e32 v38, v38
	v_mul_f32_e32 v39, 0xbfb8aa3b, v49
	v_exp_f32_e32 v39, v39
	v_cvt_pk_bf16_f32 v34, v34, v35
	v_add_f32_e32 v38, 1.0, v38
	v_rcp_f32_e32 v38, v38
	v_add_f32_e32 v39, 1.0, v39
	v_rcp_f32_e32 v39, v39
	v_mul_f32_e32 v35, v48, v40
	v_mul_f32_e32 v35, v35, v38
	v_mul_f32_e32 v38, v49, v41
	v_pk_mul_f32 v[42:43], v[42:43], v[52:53] op_sel_hi:[1,0]
	v_mul_f32_e32 v38, v38, v39
	v_cvt_pk_bf16_f32 v35, v35, v38
	v_mul_f32_e32 v38, 0xbfb8aa3b, v42
	v_exp_f32_e32 v38, v38
	v_mul_f32_e32 v36, v42, v36
	v_pk_mul_f32 v[44:45], v[44:45], v[52:53] op_sel_hi:[1,0]
	v_mul_f32_e32 v37, v43, v37
	v_add_f32_e32 v38, 1.0, v38
	v_rcp_f32_e32 v38, v38
	v_mul_f32_e32 v39, 0xbfb8aa3b, v45
	v_exp_f32_e32 v39, v39
	v_add_u32_e32 v50, 0x90, v151
	v_mul_f32_e32 v36, v36, v38
	v_mul_f32_e32 v38, 0xbfb8aa3b, v43
	v_exp_f32_e32 v38, v38
	v_add_f32_e32 v39, 1.0, v39
	v_rcp_f32_e32 v39, v39
	v_mad_i64_i32 v[50:51], s[8:9], v50, s26, v[140:141]
	v_add_f32_e32 v38, 1.0, v38
	v_rcp_f32_e32 v38, v38
	v_lshl_add_u64 v[50:51], v[50:51], 0, v[142:143]
	v_mul_f32_e32 v37, v37, v38
	v_mul_f32_e32 v38, 0xbfb8aa3b, v44
	v_exp_f32_e32 v38, v38
	v_cvt_pk_bf16_f32 v36, v36, v37
	v_mul_f32_e32 v37, v44, v54
	v_add_f32_e32 v38, 1.0, v38
	v_rcp_f32_e32 v38, v38
	s_nop 0
	v_mul_f32_e32 v37, v37, v38
	v_mul_f32_e32 v38, v45, v55
	v_mul_f32_e32 v38, v38, v39
	v_cvt_pk_bf16_f32 v37, v37, v38
	global_store_dwordx4 v[50:51], v[34:37], off nt
	ds_read_b32 v36, v152 offset:640
	s_waitcnt lgkmcnt(0)
	v_pk_mul_f32 v[30:31], v[30:31], v[36:37] op_sel_hi:[1,0]
	v_pk_mul_f32 v[22:23], v[22:23], v[36:37] op_sel_hi:[1,0]
	v_pk_mul_f32 v[38:39], v[20:21], v[36:37] op_sel_hi:[1,0]
	v_pk_mul_f32 v[20:21], v[18:19], v[36:37] op_sel_hi:[1,0]
	v_mul_f32_e32 v19, 0xbfb8aa3b, v30
	v_mul_f32_e32 v18, v30, v22
	v_exp_f32_e32 v19, v19
	v_mul_f32_e32 v22, 0xbfb8aa3b, v31
	v_exp_f32_e32 v22, v22
	v_pk_mul_f32 v[32:33], v[32:33], v[36:37] op_sel_hi:[1,0]
	v_add_f32_e32 v19, 1.0, v19
	v_rcp_f32_e32 v19, v19
	v_add_f32_e32 v22, 1.0, v22
	v_rcp_f32_e32 v22, v22
	v_pk_mul_f32 v[24:25], v[24:25], v[36:37] op_sel_hi:[1,0]
	v_mul_f32_e32 v18, v18, v19
	v_mul_f32_e32 v19, v31, v23
	v_mul_f32_e32 v19, v19, v22
	v_mul_f32_e32 v22, 0xbfb8aa3b, v32
	v_exp_f32_e32 v22, v22
	v_mul_f32_e32 v23, 0xbfb8aa3b, v33
	v_exp_f32_e32 v23, v23
	v_cvt_pk_bf16_f32 v18, v18, v19
	v_add_f32_e32 v22, 1.0, v22
	v_rcp_f32_e32 v22, v22
	v_add_f32_e32 v23, 1.0, v23
	v_rcp_f32_e32 v23, v23
	v_mul_f32_e32 v19, v32, v24
	v_mul_f32_e32 v19, v19, v22
	v_mul_f32_e32 v22, v33, v25
	v_pk_mul_f32 v[26:27], v[26:27], v[36:37] op_sel_hi:[1,0]
	v_mul_f32_e32 v22, v22, v23
	v_cvt_pk_bf16_f32 v19, v19, v22
	v_mul_f32_e32 v22, 0xbfb8aa3b, v26
	v_exp_f32_e32 v22, v22
	v_mul_f32_e32 v20, v26, v20
	v_pk_mul_f32 v[28:29], v[28:29], v[36:37] op_sel_hi:[1,0]
	v_mul_f32_e32 v21, v27, v21
	v_add_f32_e32 v22, 1.0, v22
	v_rcp_f32_e32 v22, v22
	v_mul_f32_e32 v23, 0xbfb8aa3b, v29
	v_exp_f32_e32 v23, v23
	v_add_u32_e32 v34, 0xa0, v151
	v_mul_f32_e32 v20, v20, v22
	v_mul_f32_e32 v22, 0xbfb8aa3b, v27
	v_exp_f32_e32 v22, v22
	v_add_f32_e32 v23, 1.0, v23
	v_rcp_f32_e32 v23, v23
	v_mad_i64_i32 v[34:35], s[8:9], v34, s26, v[140:141]
	v_add_f32_e32 v22, 1.0, v22
	v_rcp_f32_e32 v22, v22
	v_lshl_add_u64 v[34:35], v[34:35], 0, v[142:143]
	v_mul_f32_e32 v21, v21, v22
	v_mul_f32_e32 v22, 0xbfb8aa3b, v28
	v_exp_f32_e32 v22, v22
	v_cvt_pk_bf16_f32 v20, v20, v21
	v_mul_f32_e32 v21, v28, v38
	v_add_f32_e32 v22, 1.0, v22
	v_rcp_f32_e32 v22, v22
	s_nop 0
	v_mul_f32_e32 v21, v21, v22
	v_mul_f32_e32 v22, v29, v39
	v_mul_f32_e32 v22, v22, v23
	v_cvt_pk_bf16_f32 v21, v21, v22
	global_store_dwordx4 v[34:35], v[18:21], off nt
	ds_read_b32 v20, v152 offset:704
	s_waitcnt lgkmcnt(0)
	v_pk_mul_f32 v[14:15], v[14:15], v[20:21] op_sel_hi:[1,0]
	v_pk_mul_f32 v[6:7], v[6:7], v[20:21] op_sel_hi:[1,0]
	v_pk_mul_f32 v[22:23], v[4:5], v[20:21] op_sel_hi:[1,0]
	v_pk_mul_f32 v[4:5], v[2:3], v[20:21] op_sel_hi:[1,0]
	v_mul_f32_e32 v3, 0xbfb8aa3b, v14
	v_mul_f32_e32 v2, v14, v6
	v_exp_f32_e32 v3, v3
	v_mul_f32_e32 v6, 0xbfb8aa3b, v15
	v_exp_f32_e32 v6, v6
	v_pk_mul_f32 v[16:17], v[16:17], v[20:21] op_sel_hi:[1,0]
	v_add_f32_e32 v3, 1.0, v3
	v_rcp_f32_e32 v3, v3
	v_add_f32_e32 v6, 1.0, v6
	v_rcp_f32_e32 v6, v6
	v_pk_mul_f32 v[8:9], v[8:9], v[20:21] op_sel_hi:[1,0]
	v_mul_f32_e32 v2, v2, v3
	v_mul_f32_e32 v3, v15, v7
	v_mul_f32_e32 v3, v3, v6
	v_mul_f32_e32 v6, 0xbfb8aa3b, v16
	v_exp_f32_e32 v6, v6
	v_mul_f32_e32 v7, 0xbfb8aa3b, v17
	v_exp_f32_e32 v7, v7
	v_cvt_pk_bf16_f32 v2, v2, v3
	v_add_f32_e32 v6, 1.0, v6
	v_rcp_f32_e32 v6, v6
	v_add_f32_e32 v7, 1.0, v7
	v_rcp_f32_e32 v7, v7
	v_mul_f32_e32 v3, v16, v8
	v_mul_f32_e32 v3, v3, v6
	v_mul_f32_e32 v6, v17, v9
	v_pk_mul_f32 v[10:11], v[10:11], v[20:21] op_sel_hi:[1,0]
	v_mul_f32_e32 v6, v6, v7
	v_cvt_pk_bf16_f32 v3, v3, v6
	v_mul_f32_e32 v6, 0xbfb8aa3b, v10
	v_exp_f32_e32 v6, v6
	v_mul_f32_e32 v4, v10, v4
	v_pk_mul_f32 v[12:13], v[12:13], v[20:21] op_sel_hi:[1,0]
	v_mul_f32_e32 v5, v11, v5
	v_add_f32_e32 v6, 1.0, v6
	v_rcp_f32_e32 v6, v6
	v_mul_f32_e32 v7, 0xbfb8aa3b, v13
	v_exp_f32_e32 v7, v7
	v_add_u32_e32 v18, 0xb0, v151
	v_mul_f32_e32 v4, v4, v6
	v_mul_f32_e32 v6, 0xbfb8aa3b, v11
	v_exp_f32_e32 v6, v6
	v_add_f32_e32 v7, 1.0, v7
	v_rcp_f32_e32 v7, v7
	v_mad_i64_i32 v[18:19], s[8:9], v18, s26, v[140:141]
	v_add_f32_e32 v6, 1.0, v6
	v_rcp_f32_e32 v6, v6
	v_lshl_add_u64 v[18:19], v[18:19], 0, v[142:143]
	v_mul_f32_e32 v5, v5, v6
	v_mul_f32_e32 v6, 0xbfb8aa3b, v12
	v_exp_f32_e32 v6, v6
	v_cvt_pk_bf16_f32 v4, v4, v5
	v_mul_f32_e32 v5, v12, v22
	v_add_f32_e32 v6, 1.0, v6
	v_rcp_f32_e32 v6, v6
	s_nop 0
	v_mul_f32_e32 v5, v5, v6
	v_mul_f32_e32 v6, v13, v23
	v_mul_f32_e32 v6, v6, v7
	v_cvt_pk_bf16_f32 v5, v5, v6
	global_store_dwordx4 v[18:19], v[2:5], off nt
	s_cbranch_vccnz .LBB0_506
	s_andn2_b64 vcc, exec, s[0:1]
	s_cbranch_vccnz .LBB0_505
	s_barrier
	s_branch .LBB0_505
